# k23: k22 + PRO x->xb/ssq row pass unrolled x4 with all 32 row loads issued up front (4 register sets), counted vmcnt per set
# baseline (speedup 1.0000x reference)
.LBB0_127:
	s_waitcnt lgkmcnt(0)
	v_lshl_add_u64 v[72:73], v[6:7], 0, s[16:17]
	global_load_dwordx4 v[68:71], v[6:7], off offset:-2048 nt
	s_nop 0
	global_load_dwordx4 v[72:75], v[72:73], off offset:16 nt
	s_nop 0
	global_load_dwordx4 v[76:79], v[6:7], off offset:-2064 nt
	v_add_co_u32_e32 v92, vcc, 0xfffff000, v6
	s_nop 0
	v_addc_co_u32_e32 v93, vcc, -1, v7, vcc
	global_load_dwordx4 v[80:83], v[92:93], off offset:-2064 nt
	global_load_dwordx4 v[84:87], v[6:7], off offset:-16 nt
	global_load_dwordx4 v[88:91], v[6:7], off nt
	s_nop 0
	global_load_dwordx4 v[92:95], v[92:93], off offset:-16 nt
	s_nop 0
	global_load_dwordx4 v[96:99], v[6:7], off offset:-4096 nt
	v_lshl_add_u64 v[6:7], v[6:7], 0, s[14:15]
	v_lshl_add_u64 v[104:105], v[6:7], 0, s[16:17]
	global_load_dwordx4 v[100:103], v[6:7], off offset:-2048 nt
	s_nop 0
	global_load_dwordx4 v[104:107], v[104:105], off offset:16 nt
	s_nop 0
	global_load_dwordx4 v[108:111], v[6:7], off offset:-2064 nt
	v_add_co_u32_e32 v124, vcc, 0xfffff000, v6
	s_nop 0
	v_addc_co_u32_e32 v125, vcc, -1, v7, vcc
	global_load_dwordx4 v[112:115], v[124:125], off offset:-2064 nt
	global_load_dwordx4 v[116:119], v[6:7], off offset:-16 nt
	global_load_dwordx4 v[120:123], v[6:7], off nt
	s_nop 0
	global_load_dwordx4 v[124:127], v[124:125], off offset:-16 nt
	s_nop 0
	global_load_dwordx4 v[128:131], v[6:7], off offset:-4096 nt
	v_lshl_add_u64 v[6:7], v[6:7], 0, s[14:15]
	v_lshl_add_u64 v[136:137], v[6:7], 0, s[16:17]
	global_load_dwordx4 v[132:135], v[6:7], off offset:-2048 nt
	s_nop 0
	global_load_dwordx4 v[136:139], v[136:137], off offset:16 nt
	s_nop 0
	global_load_dwordx4 v[140:143], v[6:7], off offset:-2064 nt
	v_add_co_u32_e32 v156, vcc, 0xfffff000, v6
	s_nop 0
	v_addc_co_u32_e32 v157, vcc, -1, v7, vcc
	global_load_dwordx4 v[144:147], v[156:157], off offset:-2064 nt
	global_load_dwordx4 v[148:151], v[6:7], off offset:-16 nt
	global_load_dwordx4 v[152:155], v[6:7], off nt
	s_nop 0
	global_load_dwordx4 v[156:159], v[156:157], off offset:-16 nt
	s_nop 0
	global_load_dwordx4 v[160:163], v[6:7], off offset:-4096 nt
	v_lshl_add_u64 v[6:7], v[6:7], 0, s[14:15]
	v_lshl_add_u64 v[168:169], v[6:7], 0, s[16:17]
	global_load_dwordx4 v[164:167], v[6:7], off offset:-2048 nt
	s_nop 0
	global_load_dwordx4 v[168:171], v[168:169], off offset:16 nt
	s_nop 0
	global_load_dwordx4 v[172:175], v[6:7], off offset:-2064 nt
	v_add_co_u32_e32 v188, vcc, 0xfffff000, v6
	s_nop 0
	v_addc_co_u32_e32 v189, vcc, -1, v7, vcc
	global_load_dwordx4 v[176:179], v[188:189], off offset:-2064 nt
	global_load_dwordx4 v[180:183], v[6:7], off offset:-16 nt
	global_load_dwordx4 v[184:187], v[6:7], off nt
	s_nop 0
	global_load_dwordx4 v[188:191], v[188:189], off offset:-16 nt
	s_nop 0
	global_load_dwordx4 v[192:195], v[6:7], off offset:-4096 nt
	s_waitcnt vmcnt(24)
	v_lshl_add_u64 v[48:49], s[72:73], 0, v[4:5]
	v_cmp_lt_i32_e32 vcc, v10, v9
	v_pk_mul_f32 v[58:59], v[74:75], v[74:75]
	v_cndmask_b32_e32 v50, v8, v10, vcc
	v_cmp_lt_i32_e32 vcc, v11, v9
	v_lshlrev_b32_e32 v62, 2, v50
	v_pk_mul_f32 v[60:61], v[72:73], v[72:73]
	v_cndmask_b32_e32 v51, v8, v11, vcc
	v_cmp_lt_i32_e32 vcc, v12, v9
	v_lshlrev_b32_e32 v63, 2, v51
	v_pk_mul_f32 v[50:51], v[68:69], v[68:69]
	v_cndmask_b32_e32 v54, v8, v12, vcc
	v_cmp_lt_i32_e32 vcc, v13, v9
	v_lshlrev_b32_e32 v64, 2, v54
	s_nop 0
	v_cndmask_b32_e32 v55, v8, v13, vcc
	v_cmp_lt_i32_e32 vcc, v14, v9
	v_lshlrev_b32_e32 v65, 2, v55
	s_nop 0
	v_cndmask_b32_e32 v56, v8, v14, vcc
	v_cmp_lt_i32_e32 vcc, v15, v9
	v_lshlrev_b32_e32 v66, 2, v56
	s_nop 0
	v_cndmask_b32_e32 v57, v8, v15, vcc
	v_add_co_u32_e32 v52, vcc, s0, v48
	v_lshlrev_b32_e32 v67, 2, v57
	s_nop 0
	v_addc_co_u32_e32 v53, vcc, 0, v49, vcc
	v_pk_mul_f32 v[48:49], v[70:71], v[70:71]
	v_pk_fma_f32 v[56:57], v[76:77], v[76:77], v[50:51]
	v_pk_fma_f32 v[54:55], v[78:79], v[78:79], v[48:49]
	v_cvt_pk_bf16_f32 v48, v80, v81
	v_cvt_pk_bf16_f32 v49, v82, v83
	v_cvt_pk_bf16_f32 v50, v72, v73
	v_cvt_pk_bf16_f32 v51, v74, v75
	v_pk_fma_f32 v[74:75], v[84:85], v[84:85], v[56:57]
	v_pk_fma_f32 v[72:73], v[86:87], v[86:87], v[54:55]
	v_pk_fma_f32 v[82:83], v[82:83], v[82:83], v[58:59]
	v_pk_fma_f32 v[80:81], v[80:81], v[80:81], v[60:61]
	v_pk_fma_f32 v[72:73], v[90:91], v[90:91], v[72:73]
	v_pk_fma_f32 v[74:75], v[88:89], v[88:89], v[74:75]
	v_pk_fma_f32 v[82:83], v[94:95], v[94:95], v[82:83]
	v_pk_fma_f32 v[80:81], v[92:93], v[92:93], v[80:81]
	global_store_dwordx4 v[52:53], v[48:51], off
	s_nop 1
	v_add_f32_e32 v48, v74, v75
	v_add_f32_e32 v49, v72, v73
	v_pk_fma_f32 v[72:73], v[98:99], v[98:99], v[82:83]
	v_pk_fma_f32 v[74:75], v[96:97], v[96:97], v[80:81]
	v_add_f32_e32 v72, v72, v73
	v_add_f32_e32 v74, v74, v75
	v_add_f32_e32 v80, v48, v49
	v_add_f32_e32 v74, v74, v72
	ds_bpermute_b32 v75, v62, v80
	ds_bpermute_b32 v81, v62, v74
	v_cvt_pk_bf16_f32 v72, v92, v93
	v_cvt_pk_bf16_f32 v73, v94, v95
	s_waitcnt lgkmcnt(1)
	v_add_f32_e32 v80, v80, v75
	s_waitcnt lgkmcnt(0)
	v_add_f32_e32 v81, v74, v81
	ds_bpermute_b32 v82, v63, v80
	ds_bpermute_b32 v83, v63, v81
	v_cvt_pk_bf16_f32 v74, v96, v97
	v_cvt_pk_bf16_f32 v75, v98, v99
	global_store_dwordx4 v[52:53], v[72:75], off offset:1024
	s_waitcnt lgkmcnt(1)
	v_add_f32_e32 v80, v80, v82
	s_waitcnt lgkmcnt(0)
	v_add_f32_e32 v81, v81, v83
	ds_bpermute_b32 v82, v64, v80
	ds_bpermute_b32 v83, v64, v81
	v_cvt_pk_bf16_f32 v72, v76, v77
	v_cvt_pk_bf16_f32 v73, v78, v79
	v_cvt_pk_bf16_f32 v74, v68, v69
	s_waitcnt lgkmcnt(1)
	v_add_f32_e32 v75, v80, v82
	s_waitcnt lgkmcnt(0)
	v_add_f32_e32 v77, v81, v83
	ds_bpermute_b32 v76, v65, v75
	ds_bpermute_b32 v80, v65, v77
	s_waitcnt lgkmcnt(1)
	v_add_f32_e32 v68, v75, v76
	s_waitcnt lgkmcnt(0)
	v_add_f32_e32 v76, v77, v80
	ds_bpermute_b32 v69, v66, v68
	ds_bpermute_b32 v77, v66, v76
	v_cvt_pk_bf16_f32 v75, v70, v71
	global_store_dwordx4 v[52:53], v[72:75], off offset:2048
	s_waitcnt lgkmcnt(1)
	v_add_f32_e32 v69, v68, v69
	s_waitcnt lgkmcnt(0)
	v_add_f32_e32 v68, v76, v77
	ds_bpermute_b32 v70, v67, v68
	ds_bpermute_b32 v71, v67, v69
	v_cvt_pk_bf16_f32 v72, v84, v85
	v_cvt_pk_bf16_f32 v73, v86, v87
	v_cvt_pk_bf16_f32 v74, v88, v89
	v_cvt_pk_bf16_f32 v75, v90, v91
	global_store_dwordx4 v[52:53], v[72:75], off offset:3072
	s_and_saveexec_b64 s[18:19], s[4:5]

	s_waitcnt lgkmcnt(0)
	v_add_f32_e32 v71, v69, v71
	v_add_f32_e32 v70, v68, v70
	v_cndmask_b32_e64 v71, 0, v71, s[8:9]
	v_lshl_add_u64 v[68:69], s[72:73], 0, v[2:3]
	v_cndmask_b32_e64 v70, v71, v70, s[6:7]
	global_store_dword v[68:69], v70, off
	s_or_b64 exec, exec, s[18:19]
	v_lshl_add_u64 v[2:3], v[2:3], 0, s[10:11]
	v_lshl_add_u64 v[4:5], v[4:5], 0, s[12:13]
	s_waitcnt vmcnt(21)
	v_lshl_add_u64 v[48:49], s[72:73], 0, v[4:5]
	v_cmp_lt_i32_e32 vcc, v10, v9
	v_pk_mul_f32 v[58:59], v[106:107], v[106:107]
	v_cndmask_b32_e32 v50, v8, v10, vcc
	v_cmp_lt_i32_e32 vcc, v11, v9
	v_lshlrev_b32_e32 v62, 2, v50
	v_pk_mul_f32 v[60:61], v[104:105], v[104:105]
	v_cndmask_b32_e32 v51, v8, v11, vcc
	v_cmp_lt_i32_e32 vcc, v12, v9
	v_lshlrev_b32_e32 v63, 2, v51
	v_pk_mul_f32 v[50:51], v[100:101], v[100:101]
	v_cndmask_b32_e32 v54, v8, v12, vcc
	v_cmp_lt_i32_e32 vcc, v13, v9
	v_lshlrev_b32_e32 v64, 2, v54
	s_nop 0
	v_cndmask_b32_e32 v55, v8, v13, vcc
	v_cmp_lt_i32_e32 vcc, v14, v9
	v_lshlrev_b32_e32 v65, 2, v55
	s_nop 0
	v_cndmask_b32_e32 v56, v8, v14, vcc
	v_cmp_lt_i32_e32 vcc, v15, v9
	v_lshlrev_b32_e32 v66, 2, v56
	s_nop 0
	v_cndmask_b32_e32 v57, v8, v15, vcc
	v_add_co_u32_e32 v52, vcc, s0, v48
	v_lshlrev_b32_e32 v67, 2, v57
	s_nop 0
	v_addc_co_u32_e32 v53, vcc, 0, v49, vcc
	v_pk_mul_f32 v[48:49], v[102:103], v[102:103]
	v_pk_fma_f32 v[56:57], v[108:109], v[108:109], v[50:51]
	v_pk_fma_f32 v[54:55], v[110:111], v[110:111], v[48:49]
	v_cvt_pk_bf16_f32 v48, v112, v113
	v_cvt_pk_bf16_f32 v49, v114, v115
	v_cvt_pk_bf16_f32 v50, v104, v105
	v_cvt_pk_bf16_f32 v51, v106, v107
	v_pk_fma_f32 v[106:107], v[116:117], v[116:117], v[56:57]
	v_pk_fma_f32 v[104:105], v[118:119], v[118:119], v[54:55]
	v_pk_fma_f32 v[114:115], v[114:115], v[114:115], v[58:59]
	v_pk_fma_f32 v[112:113], v[112:113], v[112:113], v[60:61]
	v_pk_fma_f32 v[104:105], v[122:123], v[122:123], v[104:105]
	v_pk_fma_f32 v[106:107], v[120:121], v[120:121], v[106:107]
	v_pk_fma_f32 v[114:115], v[126:127], v[126:127], v[114:115]
	v_pk_fma_f32 v[112:113], v[124:125], v[124:125], v[112:113]
	global_store_dwordx4 v[52:53], v[48:51], off
	s_nop 1
	v_add_f32_e32 v48, v106, v107
	v_add_f32_e32 v49, v104, v105
	v_pk_fma_f32 v[104:105], v[130:131], v[130:131], v[114:115]
	v_pk_fma_f32 v[106:107], v[128:129], v[128:129], v[112:113]
	v_add_f32_e32 v104, v104, v105
	v_add_f32_e32 v106, v106, v107
	v_add_f32_e32 v112, v48, v49
	v_add_f32_e32 v106, v106, v104
	ds_bpermute_b32 v107, v62, v112
	ds_bpermute_b32 v113, v62, v106
	v_cvt_pk_bf16_f32 v104, v124, v125
	v_cvt_pk_bf16_f32 v105, v126, v127
	s_waitcnt lgkmcnt(1)
	v_add_f32_e32 v112, v112, v107
	s_waitcnt lgkmcnt(0)
	v_add_f32_e32 v113, v106, v113
	ds_bpermute_b32 v114, v63, v112
	ds_bpermute_b32 v115, v63, v113
	v_cvt_pk_bf16_f32 v106, v128, v129
	v_cvt_pk_bf16_f32 v107, v130, v131
	global_store_dwordx4 v[52:53], v[104:107], off offset:1024
	s_waitcnt lgkmcnt(1)
	v_add_f32_e32 v112, v112, v114
	s_waitcnt lgkmcnt(0)
	v_add_f32_e32 v113, v113, v115
	ds_bpermute_b32 v114, v64, v112
	ds_bpermute_b32 v115, v64, v113
	v_cvt_pk_bf16_f32 v104, v108, v109
	v_cvt_pk_bf16_f32 v105, v110, v111
	v_cvt_pk_bf16_f32 v106, v100, v101
	s_waitcnt lgkmcnt(1)
	v_add_f32_e32 v107, v112, v114
	s_waitcnt lgkmcnt(0)
	v_add_f32_e32 v109, v113, v115
	ds_bpermute_b32 v108, v65, v107
	ds_bpermute_b32 v112, v65, v109
	s_waitcnt lgkmcnt(1)
	v_add_f32_e32 v100, v107, v108
	s_waitcnt lgkmcnt(0)
	v_add_f32_e32 v108, v109, v112
	ds_bpermute_b32 v101, v66, v100
	ds_bpermute_b32 v109, v66, v108
	v_cvt_pk_bf16_f32 v107, v102, v103
	global_store_dwordx4 v[52:53], v[104:107], off offset:2048
	s_waitcnt lgkmcnt(1)
	v_add_f32_e32 v101, v100, v101
	s_waitcnt lgkmcnt(0)
	v_add_f32_e32 v100, v108, v109
	ds_bpermute_b32 v102, v67, v100
	ds_bpermute_b32 v103, v67, v101
	v_cvt_pk_bf16_f32 v104, v116, v117
	v_cvt_pk_bf16_f32 v105, v118, v119
	v_cvt_pk_bf16_f32 v106, v120, v121
	v_cvt_pk_bf16_f32 v107, v122, v123
	global_store_dwordx4 v[52:53], v[104:107], off offset:3072
	s_and_saveexec_b64 s[18:19], s[4:5]

	s_waitcnt lgkmcnt(0)
	v_add_f32_e32 v103, v101, v103
	v_add_f32_e32 v102, v100, v102
	v_cndmask_b32_e64 v103, 0, v103, s[8:9]
	v_lshl_add_u64 v[100:101], s[72:73], 0, v[2:3]
	v_cndmask_b32_e64 v102, v103, v102, s[6:7]
	global_store_dword v[100:101], v102, off
	s_or_b64 exec, exec, s[18:19]
	v_lshl_add_u64 v[2:3], v[2:3], 0, s[10:11]
	v_lshl_add_u64 v[4:5], v[4:5], 0, s[12:13]
	s_waitcnt vmcnt(18)
	v_lshl_add_u64 v[48:49], s[72:73], 0, v[4:5]
	v_cmp_lt_i32_e32 vcc, v10, v9
	v_pk_mul_f32 v[58:59], v[138:139], v[138:139]
	v_cndmask_b32_e32 v50, v8, v10, vcc
	v_cmp_lt_i32_e32 vcc, v11, v9
	v_lshlrev_b32_e32 v62, 2, v50
	v_pk_mul_f32 v[60:61], v[136:137], v[136:137]
	v_cndmask_b32_e32 v51, v8, v11, vcc
	v_cmp_lt_i32_e32 vcc, v12, v9
	v_lshlrev_b32_e32 v63, 2, v51
	v_pk_mul_f32 v[50:51], v[132:133], v[132:133]
	v_cndmask_b32_e32 v54, v8, v12, vcc
	v_cmp_lt_i32_e32 vcc, v13, v9
	v_lshlrev_b32_e32 v64, 2, v54
	s_nop 0
	v_cndmask_b32_e32 v55, v8, v13, vcc
	v_cmp_lt_i32_e32 vcc, v14, v9
	v_lshlrev_b32_e32 v65, 2, v55
	s_nop 0
	v_cndmask_b32_e32 v56, v8, v14, vcc
	v_cmp_lt_i32_e32 vcc, v15, v9
	v_lshlrev_b32_e32 v66, 2, v56
	s_nop 0
	v_cndmask_b32_e32 v57, v8, v15, vcc
	v_add_co_u32_e32 v52, vcc, s0, v48
	v_lshlrev_b32_e32 v67, 2, v57
	s_nop 0
	v_addc_co_u32_e32 v53, vcc, 0, v49, vcc
	v_pk_mul_f32 v[48:49], v[134:135], v[134:135]
	v_pk_fma_f32 v[56:57], v[140:141], v[140:141], v[50:51]
	v_pk_fma_f32 v[54:55], v[142:143], v[142:143], v[48:49]
	v_cvt_pk_bf16_f32 v48, v144, v145
	v_cvt_pk_bf16_f32 v49, v146, v147
	v_cvt_pk_bf16_f32 v50, v136, v137
	v_cvt_pk_bf16_f32 v51, v138, v139
	v_pk_fma_f32 v[138:139], v[148:149], v[148:149], v[56:57]
	v_pk_fma_f32 v[136:137], v[150:151], v[150:151], v[54:55]
	v_pk_fma_f32 v[146:147], v[146:147], v[146:147], v[58:59]
	v_pk_fma_f32 v[144:145], v[144:145], v[144:145], v[60:61]
	v_pk_fma_f32 v[136:137], v[154:155], v[154:155], v[136:137]
	v_pk_fma_f32 v[138:139], v[152:153], v[152:153], v[138:139]
	v_pk_fma_f32 v[146:147], v[158:159], v[158:159], v[146:147]
	v_pk_fma_f32 v[144:145], v[156:157], v[156:157], v[144:145]
	global_store_dwordx4 v[52:53], v[48:51], off
	s_nop 1
	v_add_f32_e32 v48, v138, v139
	v_add_f32_e32 v49, v136, v137
	v_pk_fma_f32 v[136:137], v[162:163], v[162:163], v[146:147]
	v_pk_fma_f32 v[138:139], v[160:161], v[160:161], v[144:145]
	v_add_f32_e32 v136, v136, v137
	v_add_f32_e32 v138, v138, v139
	v_add_f32_e32 v144, v48, v49
	v_add_f32_e32 v138, v138, v136
	ds_bpermute_b32 v139, v62, v144
	ds_bpermute_b32 v145, v62, v138
	v_cvt_pk_bf16_f32 v136, v156, v157
	v_cvt_pk_bf16_f32 v137, v158, v159
	s_waitcnt lgkmcnt(1)
	v_add_f32_e32 v144, v144, v139
	s_waitcnt lgkmcnt(0)
	v_add_f32_e32 v145, v138, v145
	ds_bpermute_b32 v146, v63, v144
	ds_bpermute_b32 v147, v63, v145
	v_cvt_pk_bf16_f32 v138, v160, v161
	v_cvt_pk_bf16_f32 v139, v162, v163
	global_store_dwordx4 v[52:53], v[136:139], off offset:1024
	s_waitcnt lgkmcnt(1)
	v_add_f32_e32 v144, v144, v146
	s_waitcnt lgkmcnt(0)
	v_add_f32_e32 v145, v145, v147
	ds_bpermute_b32 v146, v64, v144
	ds_bpermute_b32 v147, v64, v145
	v_cvt_pk_bf16_f32 v136, v140, v141
	v_cvt_pk_bf16_f32 v137, v142, v143
	v_cvt_pk_bf16_f32 v138, v132, v133
	s_waitcnt lgkmcnt(1)
	v_add_f32_e32 v139, v144, v146
	s_waitcnt lgkmcnt(0)
	v_add_f32_e32 v141, v145, v147
	ds_bpermute_b32 v140, v65, v139
	ds_bpermute_b32 v144, v65, v141
	s_waitcnt lgkmcnt(1)
	v_add_f32_e32 v132, v139, v140
	s_waitcnt lgkmcnt(0)
	v_add_f32_e32 v140, v141, v144
	ds_bpermute_b32 v133, v66, v132
	ds_bpermute_b32 v141, v66, v140
	v_cvt_pk_bf16_f32 v139, v134, v135
	global_store_dwordx4 v[52:53], v[136:139], off offset:2048
	s_waitcnt lgkmcnt(1)
	v_add_f32_e32 v133, v132, v133
	s_waitcnt lgkmcnt(0)
	v_add_f32_e32 v132, v140, v141
	ds_bpermute_b32 v134, v67, v132
	ds_bpermute_b32 v135, v67, v133
	v_cvt_pk_bf16_f32 v136, v148, v149
	v_cvt_pk_bf16_f32 v137, v150, v151
	v_cvt_pk_bf16_f32 v138, v152, v153
	v_cvt_pk_bf16_f32 v139, v154, v155
	global_store_dwordx4 v[52:53], v[136:139], off offset:3072
	s_and_saveexec_b64 s[18:19], s[4:5]

	s_waitcnt lgkmcnt(0)
	v_add_f32_e32 v135, v133, v135
	v_add_f32_e32 v134, v132, v134
	v_cndmask_b32_e64 v135, 0, v135, s[8:9]
	v_lshl_add_u64 v[132:133], s[72:73], 0, v[2:3]
	v_cndmask_b32_e64 v134, v135, v134, s[6:7]
	global_store_dword v[132:133], v134, off
	s_or_b64 exec, exec, s[18:19]
	v_lshl_add_u64 v[2:3], v[2:3], 0, s[10:11]
	v_lshl_add_u64 v[4:5], v[4:5], 0, s[12:13]
	s_waitcnt vmcnt(15)
	v_lshl_add_u64 v[48:49], s[72:73], 0, v[4:5]
	v_cmp_lt_i32_e32 vcc, v10, v9
	v_pk_mul_f32 v[58:59], v[170:171], v[170:171]
	v_cndmask_b32_e32 v50, v8, v10, vcc
	v_cmp_lt_i32_e32 vcc, v11, v9
	v_lshlrev_b32_e32 v62, 2, v50
	v_pk_mul_f32 v[60:61], v[168:169], v[168:169]
	v_cndmask_b32_e32 v51, v8, v11, vcc
	v_cmp_lt_i32_e32 vcc, v12, v9
	v_lshlrev_b32_e32 v63, 2, v51
	v_pk_mul_f32 v[50:51], v[164:165], v[164:165]
	v_cndmask_b32_e32 v54, v8, v12, vcc
	v_cmp_lt_i32_e32 vcc, v13, v9
	v_lshlrev_b32_e32 v64, 2, v54
	s_nop 0
	v_cndmask_b32_e32 v55, v8, v13, vcc
	v_cmp_lt_i32_e32 vcc, v14, v9
	v_lshlrev_b32_e32 v65, 2, v55
	s_nop 0
	v_cndmask_b32_e32 v56, v8, v14, vcc
	v_cmp_lt_i32_e32 vcc, v15, v9
	v_lshlrev_b32_e32 v66, 2, v56
	s_nop 0
	v_cndmask_b32_e32 v57, v8, v15, vcc
	v_add_co_u32_e32 v52, vcc, s0, v48
	v_lshlrev_b32_e32 v67, 2, v57
	s_nop 0
	v_addc_co_u32_e32 v53, vcc, 0, v49, vcc
	v_pk_mul_f32 v[48:49], v[166:167], v[166:167]
	v_pk_fma_f32 v[56:57], v[172:173], v[172:173], v[50:51]
	v_pk_fma_f32 v[54:55], v[174:175], v[174:175], v[48:49]
	v_cvt_pk_bf16_f32 v48, v176, v177
	v_cvt_pk_bf16_f32 v49, v178, v179
	v_cvt_pk_bf16_f32 v50, v168, v169
	v_cvt_pk_bf16_f32 v51, v170, v171
	v_pk_fma_f32 v[170:171], v[180:181], v[180:181], v[56:57]
	v_pk_fma_f32 v[168:169], v[182:183], v[182:183], v[54:55]
	v_pk_fma_f32 v[178:179], v[178:179], v[178:179], v[58:59]
	v_pk_fma_f32 v[176:177], v[176:177], v[176:177], v[60:61]
	v_pk_fma_f32 v[168:169], v[186:187], v[186:187], v[168:169]
	v_pk_fma_f32 v[170:171], v[184:185], v[184:185], v[170:171]
	v_pk_fma_f32 v[178:179], v[190:191], v[190:191], v[178:179]
	v_pk_fma_f32 v[176:177], v[188:189], v[188:189], v[176:177]
	global_store_dwordx4 v[52:53], v[48:51], off
	s_nop 1
	v_add_f32_e32 v48, v170, v171
	v_add_f32_e32 v49, v168, v169
	v_pk_fma_f32 v[168:169], v[194:195], v[194:195], v[178:179]
	v_pk_fma_f32 v[170:171], v[192:193], v[192:193], v[176:177]
	v_add_f32_e32 v168, v168, v169
	v_add_f32_e32 v170, v170, v171
	v_add_f32_e32 v176, v48, v49
	v_add_f32_e32 v170, v170, v168
	ds_bpermute_b32 v171, v62, v176
	ds_bpermute_b32 v177, v62, v170
	v_cvt_pk_bf16_f32 v168, v188, v189
	v_cvt_pk_bf16_f32 v169, v190, v191
	s_waitcnt lgkmcnt(1)
	v_add_f32_e32 v176, v176, v171
	s_waitcnt lgkmcnt(0)
	v_add_f32_e32 v177, v170, v177
	ds_bpermute_b32 v178, v63, v176
	ds_bpermute_b32 v179, v63, v177
	v_cvt_pk_bf16_f32 v170, v192, v193
	v_cvt_pk_bf16_f32 v171, v194, v195
	global_store_dwordx4 v[52:53], v[168:171], off offset:1024
	s_waitcnt lgkmcnt(1)
	v_add_f32_e32 v176, v176, v178
	s_waitcnt lgkmcnt(0)
	v_add_f32_e32 v177, v177, v179
	ds_bpermute_b32 v178, v64, v176
	ds_bpermute_b32 v179, v64, v177
	v_cvt_pk_bf16_f32 v168, v172, v173
	v_cvt_pk_bf16_f32 v169, v174, v175
	v_cvt_pk_bf16_f32 v170, v164, v165
	s_waitcnt lgkmcnt(1)
	v_add_f32_e32 v171, v176, v178
	s_waitcnt lgkmcnt(0)
	v_add_f32_e32 v173, v177, v179
	ds_bpermute_b32 v172, v65, v171
	ds_bpermute_b32 v176, v65, v173
	s_waitcnt lgkmcnt(1)
	v_add_f32_e32 v164, v171, v172
	s_waitcnt lgkmcnt(0)
	v_add_f32_e32 v172, v173, v176
	ds_bpermute_b32 v165, v66, v164
	ds_bpermute_b32 v173, v66, v172
	v_cvt_pk_bf16_f32 v171, v166, v167
	global_store_dwordx4 v[52:53], v[168:171], off offset:2048
	s_waitcnt lgkmcnt(1)
	v_add_f32_e32 v165, v164, v165
	s_waitcnt lgkmcnt(0)
	v_add_f32_e32 v164, v172, v173
	ds_bpermute_b32 v166, v67, v164
	ds_bpermute_b32 v167, v67, v165
	v_cvt_pk_bf16_f32 v168, v180, v181
	v_cvt_pk_bf16_f32 v169, v182, v183
	v_cvt_pk_bf16_f32 v170, v184, v185
	v_cvt_pk_bf16_f32 v171, v186, v187
	global_store_dwordx4 v[52:53], v[168:171], off offset:3072
	s_and_saveexec_b64 s[18:19], s[4:5]

	s_waitcnt lgkmcnt(0)
	v_add_f32_e32 v167, v165, v167
	v_add_f32_e32 v166, v164, v166
	v_cndmask_b32_e64 v167, 0, v167, s[8:9]
	v_lshl_add_u64 v[164:165], s[72:73], 0, v[2:3]
	v_cndmask_b32_e64 v166, v167, v166, s[6:7]
	global_store_dword v[164:165], v166, off
	s_or_b64 exec, exec, s[18:19]

.LBB0_201:
	s_and_b32 s99, s45, 1
	s_lshl_b32 s99, s99, 12
	v_readfirstlane_b32 s100, v0
	s_and_b32 s100, s100, 0xc0
	s_lshl_b32 s100, s100, 4
	s_add_i32 s99, s99, s100
	s_add_i32 m0, s99, 0x21000
	s_lshl_b32 s99, s26, 12
	s_add_u32 s100, s76, s99
	s_addc_u32 s101, s77, 0
	v_and_b32_e32 v129, 0xff, v0
	v_lshlrev_b32_e32 v129, 4, v129
	global_load_lds_dwordx4 v129, s[100:101]
	s_ashr_i32 s21, s20, 31
	s_lshl_b64 s[0:1], s[20:21], 19
	s_add_u32 s22, s78, s0
	s_addc_u32 s23, s79, s1
	s_and_b64 s[0:1], s[4:5], exec
	s_cselect_b32 s21, s23, s29
	s_cselect_b32 s47, s22, s28
	s_ashr_i32 s19, s18, 31
	s_lshl_b64 s[0:1], s[18:19], 19
	s_add_u32 s24, s34, s0
	s_addc_u32 s25, s35, s1
	s_and_b64 s[0:1], s[4:5], exec
	s_cselect_b32 s19, s25, s3
	s_cselect_b32 s48, s24, s2
	s_add_u32 s28, s28, 0x40080
	s_addc_u32 s29, s29, 0
	s_add_u32 s49, s2, 0x100
	v_mov_b32_e32 v2, 0
	s_addc_u32 s50, s3, 0
	s_mov_b32 s51, -2
	v_mov_b32_e32 v3, v2
	v_mov_b32_e32 v4, v2
	v_mov_b32_e32 v5, v2
	v_mov_b32_e32 v6, v2
	v_mov_b32_e32 v7, v2
	v_mov_b32_e32 v8, v2
	v_mov_b32_e32 v9, v2
	v_mov_b32_e32 v18, v2
	v_mov_b32_e32 v19, v2
	v_mov_b32_e32 v20, v2
	v_mov_b32_e32 v21, v2
	v_mov_b32_e32 v22, v2
	v_mov_b32_e32 v23, v2
	v_mov_b32_e32 v24, v2
	v_mov_b32_e32 v25, v2
	v_mov_b32_e32 v34, v2
	v_mov_b32_e32 v35, v2
	v_mov_b32_e32 v36, v2
	v_mov_b32_e32 v37, v2
	v_mov_b32_e32 v38, v2
	v_mov_b32_e32 v39, v2
	v_mov_b32_e32 v40, v2
	v_mov_b32_e32 v41, v2
	v_mov_b32_e32 v50, v2
	v_mov_b32_e32 v51, v2
	v_mov_b32_e32 v52, v2
	v_mov_b32_e32 v53, v2
	v_mov_b32_e32 v54, v2
	v_mov_b32_e32 v55, v2
	v_mov_b32_e32 v56, v2
	v_mov_b32_e32 v57, v2
	v_mov_b32_e32 v10, v2
	v_mov_b32_e32 v11, v2
	v_mov_b32_e32 v12, v2
	v_mov_b32_e32 v13, v2
	v_mov_b32_e32 v14, v2
	v_mov_b32_e32 v15, v2
	v_mov_b32_e32 v16, v2
	v_mov_b32_e32 v17, v2
	v_mov_b32_e32 v26, v2
	v_mov_b32_e32 v27, v2
	v_mov_b32_e32 v28, v2
	v_mov_b32_e32 v29, v2
	v_mov_b32_e32 v30, v2
	v_mov_b32_e32 v31, v2
	v_mov_b32_e32 v32, v2
	v_mov_b32_e32 v33, v2
	v_mov_b32_e32 v42, v2
	v_mov_b32_e32 v43, v2
	v_mov_b32_e32 v44, v2
	v_mov_b32_e32 v45, v2
	v_mov_b32_e32 v46, v2
	v_mov_b32_e32 v47, v2
	v_mov_b32_e32 v48, v2
	v_mov_b32_e32 v49, v2
	v_mov_b32_e32 v58, v2
	v_mov_b32_e32 v59, v2
	v_mov_b32_e32 v60, v2
	v_mov_b32_e32 v61, v2
	v_mov_b32_e32 v62, v2
	v_mov_b32_e32 v63, v2
	v_mov_b32_e32 v64, v2
	v_mov_b32_e32 v65, v2
	v_mov_b32_e32 v66, v2
	v_mov_b32_e32 v67, v2
	v_mov_b32_e32 v68, v2
	v_mov_b32_e32 v69, v2
	v_mov_b32_e32 v70, v2
	v_mov_b32_e32 v71, v2
	v_mov_b32_e32 v72, v2
	v_mov_b32_e32 v73, v2
	v_mov_b32_e32 v82, v2
	v_mov_b32_e32 v83, v2
	v_mov_b32_e32 v84, v2
	v_mov_b32_e32 v85, v2
	v_mov_b32_e32 v86, v2
	v_mov_b32_e32 v87, v2
	v_mov_b32_e32 v88, v2
	v_mov_b32_e32 v89, v2
	v_mov_b32_e32 v98, v2
	v_mov_b32_e32 v99, v2
	v_mov_b32_e32 v100, v2
	v_mov_b32_e32 v101, v2
	v_mov_b32_e32 v102, v2
	v_mov_b32_e32 v103, v2
	v_mov_b32_e32 v104, v2
	v_mov_b32_e32 v105, v2
	v_mov_b32_e32 v114, v2
	v_mov_b32_e32 v115, v2
	v_mov_b32_e32 v116, v2
	v_mov_b32_e32 v117, v2
	v_mov_b32_e32 v122, v2
	v_mov_b32_e32 v123, v2
	v_mov_b32_e32 v124, v2
	v_mov_b32_e32 v125, v2
	v_mov_b32_e32 v74, v2
	v_mov_b32_e32 v75, v2
	v_mov_b32_e32 v76, v2
	v_mov_b32_e32 v77, v2
	v_mov_b32_e32 v78, v2
	v_mov_b32_e32 v79, v2
	v_mov_b32_e32 v80, v2
	v_mov_b32_e32 v81, v2
	v_mov_b32_e32 v90, v2
	v_mov_b32_e32 v91, v2
	v_mov_b32_e32 v92, v2
	v_mov_b32_e32 v93, v2
	v_mov_b32_e32 v94, v2
	v_mov_b32_e32 v95, v2
	v_mov_b32_e32 v96, v2
	v_mov_b32_e32 v97, v2
	v_mov_b32_e32 v106, v2
	v_mov_b32_e32 v107, v2
	v_mov_b32_e32 v108, v2
	v_mov_b32_e32 v109, v2
	v_mov_b32_e32 v110, v2
	v_mov_b32_e32 v111, v2
	v_mov_b32_e32 v112, v2
	v_mov_b32_e32 v113, v2
	v_mov_b32_e32 v118, v2
	v_mov_b32_e32 v119, v2
	v_mov_b32_e32 v120, v2
	v_mov_b32_e32 v121, v2
	v_mov_b32_e32 v126, v2
	v_mov_b32_e32 v127, v2
	v_mov_b32_e32 v128, v2
	v_mov_b32_e32 v129, v2
	s_nop 0
	s_nop 0
	s_nop 0
	s_nop 0
	s_nop 0
	s_nop 0
	s_nop 0
	s_nop 0
	s_nop 0
	s_nop 0
	s_nop 0
